# w_up/w_down weight transposition moved out of phase 0: done by the 64 workgroups idle during the out-proj GEMM with a hand-written double-buffered tile loop
# speedup vs baseline: 1.4387x; 1.0234x over previous
.LBB0_118:
	s_add_i32 s56, s57, s3
	s_cmpk_gt_i32 s56, 0x83f
	s_cselect_b64 s[26:27], -1, 0
	s_and_b64 vcc, exec, s[26:27]
	s_cbranch_vccnz .LBB0_171
	s_cmpk_gt_i32 s56, 0x63f
	s_cselect_b64 s[4:5], -1, 0
	s_mov_b64 s[30:31], -1
	s_and_b64 vcc, exec, s[4:5]
	s_cbranch_vccnz .LBB0_121
	s_add_i32 s28, s48, s33
	s_and_b32 s58, s28, 0x7c0
	s_add_i32 s28, s50, s49
	s_and_b32 s44, s28, 0xffffff80
	s_mov_b64 s[30:31], 0
	s_mov_b64 s[28:29], s[16:17]

.LBB0_1105:
	s_load_dword s3, s[0:1], 0xa8
	s_mov_b64 s[4:5], -1
	s_waitcnt lgkmcnt(0)
	s_addk_i32 s3, 0xffb0
	s_cmp_lt_i32 s2, s3
	s_cbranch_scc1 .LBB0_1127
	s_cmpk_lt_i32 s2, 0xf0
	s_cbranch_scc0 .Lwt_skip
	s_load_dwordx2 s[18:19], s[0:1], 0x68
	s_load_dwordx2 s[20:21], s[0:1], 0x60
	s_load_dwordx2 s[22:23], s[0:1], 0x80
	s_sub_i32 s24, s2, 0xb0
	s_addk_i32 s24, 0x840
	v_lshrrev_b32_e32 v40, 5, v156
	v_and_b32_e32 v41, 31, v156
	v_lshlrev_b32_e32 v41, 4, v41
	v_mul_u32_u24_e32 v42, 0x204, v40
	v_add_u32_e32 v42, v42, v41
	v_and_b32_e32 v43, 7, v156
	v_mul_u32_u24_e32 v43, 0x1020, v43
	v_lshrrev_b32_e32 v51, 3, v156
	v_lshl_add_u32 v43, v51, 2, v43
	v_lshrrev_b32_e32 v44, 4, v51
	v_lshlrev_b32_e32 v44, 1, v44
	v_bfe_u32 v52, v156, 2, 1
	v_add_u32_e32 v44, v44, v52
	v_lshlrev_b32_e32 v44, 10, v44
	v_and_b32_e32 v52, 15, v51
	v_lshlrev_b32_e32 v52, 6, v52
	v_and_b32_e32 v53, 3, v156
	v_lshl_add_u32 v52, v53, 4, v52
	v_and_b32_e32 v53, 8, v51
	v_lshlrev_b32_e32 v53, 2, v53
	v_xor_b32_e32 v52, v52, v53
	v_add_u32_e32 v44, v44, v52
	v_add_u32_e32 v45, 0x2000, v44
	v_lshlrev_b32_e32 v50, 2, v40
	s_waitcnt lgkmcnt(0)
	s_cmpk_lt_i32 s24, 0x1340
	s_cbranch_scc0 .Lwt_down_p
	s_sub_i32 s25, s24, 0x840
	s_and_b32 s26, s25, 31
	s_lshr_b32 s27, s25, 5
	s_lshl_b32 s28, s26, 6
	s_and_b32 s29, s27, 1
	s_mul_i32 s29, s29, 0x1600
	s_lshr_b32 s30, s27, 1
	s_lshl_b32 s30, s30, 7
	s_add_i32 s29, s29, s30
	s_mul_i32 s30, s28, 0x2c00
	s_add_i32 s30, s30, s29
	s_lshl_b32 s30, s30, 2
	s_add_u32 s34, s18, s30
	s_addc_u32 s35, s19, 0
	s_lshl_b32 s31, s27, 5
	s_add_i32 s31, s31, s26
	s_mov_b32 s33, 0xb000
	s_mov_b32 s46, 1
	s_mov_b32 s30, 0x2100000
	s_branch .Lwt_dec_p
.Lwt_down_p:
	s_sub_i32 s25, s24, 0x1340
	s_mul_i32 s27, s25, 0x2e9
	s_lshr_b32 s27, s27, 16
	s_mul_i32 s26, s27, 0x58
	s_sub_i32 s26, s25, s26
	s_lshl_b32 s28, s26, 6
	s_lshl_b32 s29, s27, 7
	s_lshl_b32 s30, s28, 11
	s_add_i32 s30, s30, s29
	s_lshl_b32 s30, s30, 2
	s_add_u32 s34, s22, s30
	s_addc_u32 s35, s23, 0
	s_mul_i32 s31, s27, 0x58
	s_add_i32 s31, s31, s26
	s_mov_b32 s33, 0x2000
	s_mov_b32 s46, 0
	s_mov_b32 s30, 0x4d00000
.Lwt_dec_p:
	s_lshl_b32 s31, s31, 14
	s_add_u32 s31, s31, s30
	s_add_u32 s44, s40, s31
	s_addc_u32 s45, s41, 0
	v_mul_lo_u32 v46, v40, s33
	v_add_u32_e32 v46, v46, v41
	s_lshl_b32 s30, s33, 4
	v_add_u32_e32 v47, s30, v46
	v_add_u32_e32 v48, s30, v47
	v_add_u32_e32 v49, s30, v48
	global_load_dwordx4 v[0:3], v46, s[34:35]
	global_load_dwordx4 v[4:7], v47, s[34:35]
	global_load_dwordx4 v[8:11], v48, s[34:35]
	global_load_dwordx4 v[12:15], v49, s[34:35]
	s_and_b32 s30, s28, 0x7ff
	s_lshl_b32 s30, s30, 2
	s_add_u32 s34, s20, s30
	s_addc_u32 s35, s21, 0
	global_load_dword v16, v50, s[34:35]
	global_load_dword v17, v50, s[34:35] offset:64
	global_load_dword v18, v50, s[34:35] offset:128
	global_load_dword v19, v50, s[34:35] offset:192
	s_addk_i32 s24, 0x40
	s_cmpk_lt_i32 s24, 0x1340
	s_cbranch_scc0 .Lwt_down_q
	s_sub_i32 s25, s24, 0x840
	s_and_b32 s26, s25, 31
	s_lshr_b32 s27, s25, 5
	s_lshl_b32 s28, s26, 6
	s_and_b32 s29, s27, 1
	s_mul_i32 s29, s29, 0x1600
	s_lshr_b32 s30, s27, 1
	s_lshl_b32 s30, s30, 7
	s_add_i32 s29, s29, s30
	s_mul_i32 s30, s28, 0x2c00
	s_add_i32 s30, s30, s29
	s_lshl_b32 s30, s30, 2
	s_add_u32 s34, s18, s30
	s_addc_u32 s35, s19, 0
	s_lshl_b32 s31, s27, 5
	s_add_i32 s31, s31, s26
	s_mov_b32 s33, 0xb000
	s_mov_b32 s47, 1
	s_mov_b32 s30, 0x2100000
	s_branch .Lwt_dec_q
.Lwt_down_q:
	s_sub_i32 s25, s24, 0x1340
	s_mul_i32 s27, s25, 0x2e9
	s_lshr_b32 s27, s27, 16
	s_mul_i32 s26, s27, 0x58
	s_sub_i32 s26, s25, s26
	s_lshl_b32 s28, s26, 6
	s_lshl_b32 s29, s27, 7
	s_lshl_b32 s30, s28, 11
	s_add_i32 s30, s30, s29
	s_lshl_b32 s30, s30, 2
	s_add_u32 s34, s22, s30
	s_addc_u32 s35, s23, 0
	s_mul_i32 s31, s27, 0x58
	s_add_i32 s31, s31, s26
	s_mov_b32 s33, 0x2000
	s_mov_b32 s47, 0
	s_mov_b32 s30, 0x4d00000
.Lwt_dec_q:
	s_lshl_b32 s31, s31, 14
	s_add_u32 s31, s31, s30
	s_add_u32 s48, s40, s31
	s_addc_u32 s49, s41, 0
	v_mul_lo_u32 v46, v40, s33
	v_add_u32_e32 v46, v46, v41
	s_lshl_b32 s30, s33, 4
	v_add_u32_e32 v47, s30, v46
	v_add_u32_e32 v48, s30, v47
	v_add_u32_e32 v49, s30, v48
	global_load_dwordx4 v[20:23], v46, s[34:35]
	global_load_dwordx4 v[24:27], v47, s[34:35]
	global_load_dwordx4 v[28:31], v48, s[34:35]
	global_load_dwordx4 v[32:35], v49, s[34:35]
	s_and_b32 s30, s28, 0x7ff
	s_lshl_b32 s30, s30, 2
	s_add_u32 s34, s20, s30
	s_addc_u32 s35, s21, 0
	global_load_dword v36, v50, s[34:35]
	global_load_dword v37, v50, s[34:35] offset:64
	global_load_dword v38, v50, s[34:35] offset:128
	global_load_dword v39, v50, s[34:35] offset:192
	s_waitcnt vmcnt(8)
	s_cmp_eq_u32 s46, 0
	s_cbranch_scc1 .Lwt_nog_a0
	v_mul_f32_e32 v0, v0, v16
	v_mul_f32_e32 v1, v1, v16
	v_mul_f32_e32 v2, v2, v16
	v_mul_f32_e32 v3, v3, v16
	v_mul_f32_e32 v4, v4, v17
	v_mul_f32_e32 v5, v5, v17
	v_mul_f32_e32 v6, v6, v17
	v_mul_f32_e32 v7, v7, v17
	v_mul_f32_e32 v8, v8, v18
	v_mul_f32_e32 v9, v9, v18
	v_mul_f32_e32 v10, v10, v18
	v_mul_f32_e32 v11, v11, v18
	v_mul_f32_e32 v12, v12, v19
	v_mul_f32_e32 v13, v13, v19
	v_mul_f32_e32 v14, v14, v19
	v_mul_f32_e32 v15, v15, v19
.Lwt_nog_a0:
	ds_write_b32 v42, v0
	ds_write_b32 v42, v1 offset:4
	ds_write_b32 v42, v2 offset:8
	ds_write_b32 v42, v3 offset:12
	ds_write_b32 v42, v4 offset:8256
	ds_write_b32 v42, v5 offset:8260
	ds_write_b32 v42, v6 offset:8264
	ds_write_b32 v42, v7 offset:8268
	ds_write_b32 v42, v8 offset:16512
	ds_write_b32 v42, v9 offset:16516
	ds_write_b32 v42, v10 offset:16520
	ds_write_b32 v42, v11 offset:16524
	ds_write_b32 v42, v12 offset:24768
	ds_write_b32 v42, v13 offset:24772
	ds_write_b32 v42, v14 offset:24776
	ds_write_b32 v42, v15 offset:24780
	s_waitcnt lgkmcnt(0)
	s_barrier
	ds_read_b32 v54, v43
	ds_read_b32 v55, v43 offset:516
	ds_read_b32 v56, v43 offset:1032
	ds_read_b32 v57, v43 offset:1548
	ds_read_b32 v58, v43 offset:2064
	ds_read_b32 v59, v43 offset:2580
	ds_read_b32 v60, v43 offset:3096
	ds_read_b32 v61, v43 offset:3612
	ds_read_b32 v62, v43 offset:256
	ds_read_b32 v63, v43 offset:772
	ds_read_b32 v64, v43 offset:1288
	ds_read_b32 v65, v43 offset:1804
	ds_read_b32 v66, v43 offset:2320
	ds_read_b32 v67, v43 offset:2836
	ds_read_b32 v68, v43 offset:3352
	ds_read_b32 v69, v43 offset:3868
	s_waitcnt lgkmcnt(0)
	v_cvt_pk_bf16_f32 v72, v54, v55
	v_cvt_pk_bf16_f32 v73, v56, v57
	v_cvt_pk_bf16_f32 v74, v58, v59
	v_cvt_pk_bf16_f32 v75, v60, v61
	v_cvt_pk_bf16_f32 v76, v62, v63
	v_cvt_pk_bf16_f32 v77, v64, v65
	v_cvt_pk_bf16_f32 v78, v66, v67
	v_cvt_pk_bf16_f32 v79, v68, v69
	global_store_dwordx4 v44, v[72:75], s[44:45]
	global_store_dwordx4 v45, v[76:79], s[44:45]
	s_barrier
.Lwt_loop:
	s_addk_i32 s24, 0x40
	s_cmpk_lt_i32 s24, 0x18c0
	s_cbranch_scc0 .Lwt_lastB
	s_cmpk_lt_i32 s24, 0x1340
	s_cbranch_scc0 .Lwt_down_r
	s_sub_i32 s25, s24, 0x840
	s_and_b32 s26, s25, 31
	s_lshr_b32 s27, s25, 5
	s_lshl_b32 s28, s26, 6
	s_and_b32 s29, s27, 1
	s_mul_i32 s29, s29, 0x1600
	s_lshr_b32 s30, s27, 1
	s_lshl_b32 s30, s30, 7
	s_add_i32 s29, s29, s30
	s_mul_i32 s30, s28, 0x2c00
	s_add_i32 s30, s30, s29
	s_lshl_b32 s30, s30, 2
	s_add_u32 s34, s18, s30
	s_addc_u32 s35, s19, 0
	s_lshl_b32 s31, s27, 5
	s_add_i32 s31, s31, s26
	s_mov_b32 s33, 0xb000
	s_mov_b32 s46, 1
	s_mov_b32 s30, 0x2100000
	s_branch .Lwt_dec_r

.Lwt_dec_r:
	s_lshl_b32 s31, s31, 14
	s_add_u32 s31, s31, s30
	s_add_u32 s44, s40, s31
	s_addc_u32 s45, s41, 0
	v_mul_lo_u32 v46, v40, s33
	v_add_u32_e32 v46, v46, v41
	s_lshl_b32 s30, s33, 4
	v_add_u32_e32 v47, s30, v46
	v_add_u32_e32 v48, s30, v47
	v_add_u32_e32 v49, s30, v48
	global_load_dwordx4 v[0:3], v46, s[34:35]
	global_load_dwordx4 v[4:7], v47, s[34:35]
	global_load_dwordx4 v[8:11], v48, s[34:35]
	global_load_dwordx4 v[12:15], v49, s[34:35]
	s_and_b32 s30, s28, 0x7ff
	s_lshl_b32 s30, s30, 2
	s_add_u32 s34, s20, s30
	s_addc_u32 s35, s21, 0
	global_load_dword v16, v50, s[34:35]
	global_load_dword v17, v50, s[34:35] offset:64
	global_load_dword v18, v50, s[34:35] offset:128
	global_load_dword v19, v50, s[34:35] offset:192
	s_waitcnt vmcnt(10)
	s_cmp_eq_u32 s47, 0
	s_cbranch_scc1 .Lwt_nog_b1
	v_mul_f32_e32 v20, v20, v36
	v_mul_f32_e32 v21, v21, v36
	v_mul_f32_e32 v22, v22, v36
	v_mul_f32_e32 v23, v23, v36
	v_mul_f32_e32 v24, v24, v37
	v_mul_f32_e32 v25, v25, v37
	v_mul_f32_e32 v26, v26, v37
	v_mul_f32_e32 v27, v27, v37
	v_mul_f32_e32 v28, v28, v38
	v_mul_f32_e32 v29, v29, v38
	v_mul_f32_e32 v30, v30, v38
	v_mul_f32_e32 v31, v31, v38
	v_mul_f32_e32 v32, v32, v39
	v_mul_f32_e32 v33, v33, v39
	v_mul_f32_e32 v34, v34, v39
	v_mul_f32_e32 v35, v35, v39
.Lwt_nog_b1:
	ds_write_b32 v42, v20
	ds_write_b32 v42, v21 offset:4
	ds_write_b32 v42, v22 offset:8
	ds_write_b32 v42, v23 offset:12
	ds_write_b32 v42, v24 offset:8256
	ds_write_b32 v42, v25 offset:8260
	ds_write_b32 v42, v26 offset:8264
	ds_write_b32 v42, v27 offset:8268
	ds_write_b32 v42, v28 offset:16512
	ds_write_b32 v42, v29 offset:16516
	ds_write_b32 v42, v30 offset:16520
	ds_write_b32 v42, v31 offset:16524
	ds_write_b32 v42, v32 offset:24768
	ds_write_b32 v42, v33 offset:24772
	ds_write_b32 v42, v34 offset:24776
	ds_write_b32 v42, v35 offset:24780
	s_waitcnt lgkmcnt(0)
	s_barrier
	ds_read_b32 v54, v43
	ds_read_b32 v55, v43 offset:516
	ds_read_b32 v56, v43 offset:1032
	ds_read_b32 v57, v43 offset:1548
	ds_read_b32 v58, v43 offset:2064
	ds_read_b32 v59, v43 offset:2580
	ds_read_b32 v60, v43 offset:3096
	ds_read_b32 v61, v43 offset:3612
	ds_read_b32 v62, v43 offset:256
	ds_read_b32 v63, v43 offset:772
	ds_read_b32 v64, v43 offset:1288
	ds_read_b32 v65, v43 offset:1804
	ds_read_b32 v66, v43 offset:2320
	ds_read_b32 v67, v43 offset:2836
	ds_read_b32 v68, v43 offset:3352
	ds_read_b32 v69, v43 offset:3868
	s_waitcnt lgkmcnt(0)
	v_cvt_pk_bf16_f32 v72, v54, v55
	v_cvt_pk_bf16_f32 v73, v56, v57
	v_cvt_pk_bf16_f32 v74, v58, v59
	v_cvt_pk_bf16_f32 v75, v60, v61
	v_cvt_pk_bf16_f32 v76, v62, v63
	v_cvt_pk_bf16_f32 v77, v64, v65
	v_cvt_pk_bf16_f32 v78, v66, v67
	v_cvt_pk_bf16_f32 v79, v68, v69
	global_store_dwordx4 v44, v[72:75], s[48:49]
	global_store_dwordx4 v45, v[76:79], s[48:49]
	s_barrier
	s_addk_i32 s24, 0x40
	s_cmpk_lt_i32 s24, 0x18c0
	s_cbranch_scc0 .Lwt_lastA
	s_cmpk_lt_i32 s24, 0x1340
	s_cbranch_scc0 .Lwt_down_s
	s_sub_i32 s25, s24, 0x840
	s_and_b32 s26, s25, 31
	s_lshr_b32 s27, s25, 5
	s_lshl_b32 s28, s26, 6
	s_and_b32 s29, s27, 1
	s_mul_i32 s29, s29, 0x1600
	s_lshr_b32 s30, s27, 1
	s_lshl_b32 s30, s30, 7
	s_add_i32 s29, s29, s30
	s_mul_i32 s30, s28, 0x2c00
	s_add_i32 s30, s30, s29
	s_lshl_b32 s30, s30, 2
	s_add_u32 s34, s18, s30
	s_addc_u32 s35, s19, 0
	s_lshl_b32 s31, s27, 5
	s_add_i32 s31, s31, s26
	s_mov_b32 s33, 0xb000
	s_mov_b32 s47, 1
	s_mov_b32 s30, 0x2100000
	s_branch .Lwt_dec_s

.Lwt_dec_s:
	s_lshl_b32 s31, s31, 14
	s_add_u32 s31, s31, s30
	s_add_u32 s48, s40, s31
	s_addc_u32 s49, s41, 0
	v_mul_lo_u32 v46, v40, s33
	v_add_u32_e32 v46, v46, v41
	s_lshl_b32 s30, s33, 4
	v_add_u32_e32 v47, s30, v46
	v_add_u32_e32 v48, s30, v47
	v_add_u32_e32 v49, s30, v48
	global_load_dwordx4 v[20:23], v46, s[34:35]
	global_load_dwordx4 v[24:27], v47, s[34:35]
	global_load_dwordx4 v[28:31], v48, s[34:35]
	global_load_dwordx4 v[32:35], v49, s[34:35]
	s_and_b32 s30, s28, 0x7ff
	s_lshl_b32 s30, s30, 2
	s_add_u32 s34, s20, s30
	s_addc_u32 s35, s21, 0
	global_load_dword v36, v50, s[34:35]
	global_load_dword v37, v50, s[34:35] offset:64
	global_load_dword v38, v50, s[34:35] offset:128
	global_load_dword v39, v50, s[34:35] offset:192
	s_waitcnt vmcnt(10)
	s_cmp_eq_u32 s46, 0
	s_cbranch_scc1 .Lwt_nog_a1
	v_mul_f32_e32 v0, v0, v16
	v_mul_f32_e32 v1, v1, v16
	v_mul_f32_e32 v2, v2, v16
	v_mul_f32_e32 v3, v3, v16
	v_mul_f32_e32 v4, v4, v17
	v_mul_f32_e32 v5, v5, v17
	v_mul_f32_e32 v6, v6, v17
	v_mul_f32_e32 v7, v7, v17
	v_mul_f32_e32 v8, v8, v18
	v_mul_f32_e32 v9, v9, v18
	v_mul_f32_e32 v10, v10, v18
	v_mul_f32_e32 v11, v11, v18
	v_mul_f32_e32 v12, v12, v19
	v_mul_f32_e32 v13, v13, v19
	v_mul_f32_e32 v14, v14, v19
	v_mul_f32_e32 v15, v15, v19
.Lwt_nog_a1:
	ds_write_b32 v42, v0
	ds_write_b32 v42, v1 offset:4
	ds_write_b32 v42, v2 offset:8
	ds_write_b32 v42, v3 offset:12
	ds_write_b32 v42, v4 offset:8256
	ds_write_b32 v42, v5 offset:8260
	ds_write_b32 v42, v6 offset:8264
	ds_write_b32 v42, v7 offset:8268
	ds_write_b32 v42, v8 offset:16512
	ds_write_b32 v42, v9 offset:16516
	ds_write_b32 v42, v10 offset:16520
	ds_write_b32 v42, v11 offset:16524
	ds_write_b32 v42, v12 offset:24768
	ds_write_b32 v42, v13 offset:24772
	ds_write_b32 v42, v14 offset:24776
	ds_write_b32 v42, v15 offset:24780
	s_waitcnt lgkmcnt(0)
	s_barrier
	ds_read_b32 v54, v43
	ds_read_b32 v55, v43 offset:516
	ds_read_b32 v56, v43 offset:1032
	ds_read_b32 v57, v43 offset:1548
	ds_read_b32 v58, v43 offset:2064
	ds_read_b32 v59, v43 offset:2580
	ds_read_b32 v60, v43 offset:3096
	ds_read_b32 v61, v43 offset:3612
	ds_read_b32 v62, v43 offset:256
	ds_read_b32 v63, v43 offset:772
	ds_read_b32 v64, v43 offset:1288
	ds_read_b32 v65, v43 offset:1804
	ds_read_b32 v66, v43 offset:2320
	ds_read_b32 v67, v43 offset:2836
	ds_read_b32 v68, v43 offset:3352
	ds_read_b32 v69, v43 offset:3868
	s_waitcnt lgkmcnt(0)
	v_cvt_pk_bf16_f32 v72, v54, v55
	v_cvt_pk_bf16_f32 v73, v56, v57
	v_cvt_pk_bf16_f32 v74, v58, v59
	v_cvt_pk_bf16_f32 v75, v60, v61
	v_cvt_pk_bf16_f32 v76, v62, v63
	v_cvt_pk_bf16_f32 v77, v64, v65
	v_cvt_pk_bf16_f32 v78, v66, v67
	v_cvt_pk_bf16_f32 v79, v68, v69
	global_store_dwordx4 v44, v[72:75], s[44:45]
	global_store_dwordx4 v45, v[76:79], s[44:45]
	s_barrier
	s_branch .Lwt_loop
.Lwt_lastB:
	s_waitcnt vmcnt(0)
	s_cmp_eq_u32 s47, 0
	s_cbranch_scc1 .Lwt_nog_b2
	v_mul_f32_e32 v20, v20, v36
	v_mul_f32_e32 v21, v21, v36
	v_mul_f32_e32 v22, v22, v36
	v_mul_f32_e32 v23, v23, v36
	v_mul_f32_e32 v24, v24, v37
	v_mul_f32_e32 v25, v25, v37
	v_mul_f32_e32 v26, v26, v37
	v_mul_f32_e32 v27, v27, v37
	v_mul_f32_e32 v28, v28, v38
	v_mul_f32_e32 v29, v29, v38
	v_mul_f32_e32 v30, v30, v38
	v_mul_f32_e32 v31, v31, v38
	v_mul_f32_e32 v32, v32, v39
	v_mul_f32_e32 v33, v33, v39
	v_mul_f32_e32 v34, v34, v39
	v_mul_f32_e32 v35, v35, v39
.Lwt_nog_b2:
	ds_write_b32 v42, v20
	ds_write_b32 v42, v21 offset:4
	ds_write_b32 v42, v22 offset:8
	ds_write_b32 v42, v23 offset:12
	ds_write_b32 v42, v24 offset:8256
	ds_write_b32 v42, v25 offset:8260
	ds_write_b32 v42, v26 offset:8264
	ds_write_b32 v42, v27 offset:8268
	ds_write_b32 v42, v28 offset:16512
	ds_write_b32 v42, v29 offset:16516
	ds_write_b32 v42, v30 offset:16520
	ds_write_b32 v42, v31 offset:16524
	ds_write_b32 v42, v32 offset:24768
	ds_write_b32 v42, v33 offset:24772
	ds_write_b32 v42, v34 offset:24776
	ds_write_b32 v42, v35 offset:24780
	s_waitcnt lgkmcnt(0)
	s_barrier
	ds_read_b32 v54, v43
	ds_read_b32 v55, v43 offset:516
	ds_read_b32 v56, v43 offset:1032
	ds_read_b32 v57, v43 offset:1548
	ds_read_b32 v58, v43 offset:2064
	ds_read_b32 v59, v43 offset:2580
	ds_read_b32 v60, v43 offset:3096
	ds_read_b32 v61, v43 offset:3612
	ds_read_b32 v62, v43 offset:256
	ds_read_b32 v63, v43 offset:772
	ds_read_b32 v64, v43 offset:1288
	ds_read_b32 v65, v43 offset:1804
	ds_read_b32 v66, v43 offset:2320
	ds_read_b32 v67, v43 offset:2836
	ds_read_b32 v68, v43 offset:3352
	ds_read_b32 v69, v43 offset:3868
	s_waitcnt lgkmcnt(0)
	v_cvt_pk_bf16_f32 v72, v54, v55
	v_cvt_pk_bf16_f32 v73, v56, v57
	v_cvt_pk_bf16_f32 v74, v58, v59
	v_cvt_pk_bf16_f32 v75, v60, v61
	v_cvt_pk_bf16_f32 v76, v62, v63
	v_cvt_pk_bf16_f32 v77, v64, v65
	v_cvt_pk_bf16_f32 v78, v66, v67
	v_cvt_pk_bf16_f32 v79, v68, v69
	global_store_dwordx4 v44, v[72:75], s[48:49]
	global_store_dwordx4 v45, v[76:79], s[48:49]
	s_barrier
	s_branch .Lwt_done
.Lwt_lastA:
	s_waitcnt vmcnt(0)
	s_cmp_eq_u32 s46, 0
	s_cbranch_scc1 .Lwt_nog_a2
	v_mul_f32_e32 v0, v0, v16
	v_mul_f32_e32 v1, v1, v16
	v_mul_f32_e32 v2, v2, v16
	v_mul_f32_e32 v3, v3, v16
	v_mul_f32_e32 v4, v4, v17
	v_mul_f32_e32 v5, v5, v17
	v_mul_f32_e32 v6, v6, v17
	v_mul_f32_e32 v7, v7, v17
	v_mul_f32_e32 v8, v8, v18
	v_mul_f32_e32 v9, v9, v18
	v_mul_f32_e32 v10, v10, v18
	v_mul_f32_e32 v11, v11, v18
	v_mul_f32_e32 v12, v12, v19
	v_mul_f32_e32 v13, v13, v19
	v_mul_f32_e32 v14, v14, v19
	v_mul_f32_e32 v15, v15, v19

.Lwt_skip:
	s_load_dwordx4 s[12:15], s[0:1], 0x90
	s_cmp_eq_u32 s3, 0
	s_cselect_b64 s[10:11], -1, 0
	s_cmp_lg_u32 s3, 0
	s_cselect_b64 s[8:9], -1, 0
	s_waitcnt lgkmcnt(0)
	s_add_u32 s18, s14, 0x6330c88
	s_addc_u32 s19, s15, 0
	s_add_u32 s14, s14, 0x6330c80
	s_waitcnt vmcnt(0)
	v_or_b32_e32 v0, 0x400, v156
	s_addc_u32 s15, s15, 0
	v_or_b32_e32 v2, 0x800, v156
	v_or_b32_e32 v4, 0xc00, v156
	v_or_b32_e32 v6, 0x1000, v156
	v_or_b32_e32 v8, 0x1400, v156
	v_or_b32_e32 v10, 0x1800, v156
	v_or_b32_e32 v12, 0x1c00, v156
	v_or_b32_e32 v14, 0x2000, v156
	v_or_b32_e32 v16, 0x2400, v156
	v_or_b32_e32 v18, 0x2800, v156
	v_or_b32_e32 v20, 0x2c00, v156
	v_or_b32_e32 v22, 0x3000, v156
	v_or_b32_e32 v24, 0x3400, v156
	v_or_b32_e32 v26, 0x3800, v156
	v_or_b32_e32 v28, 0x3c00, v156
	v_or_b32_e32 v30, 0x4000, v156
	v_or_b32_e32 v32, 0x4400, v156
	v_or_b32_e32 v34, 0x4800, v156
	v_or_b32_e32 v36, 0x4c00, v156
	v_or_b32_e32 v38, 0x5000, v156
	v_or_b32_e32 v40, 0x5400, v156
	v_or_b32_e32 v42, 0x5800, v156
	v_or_b32_e32 v146, 0x7c00, v156
	s_movk_i32 s4, 0x7fc0
	s_movk_i32 s6, 0x1c0
	s_add_i32 s28, 0, 0x252f0
	v_lshlrev_b32_e32 v131, 4, v0
	v_cndmask_b32_e64 v0, 0, 1, s[8:9]
	v_mov_b32_e32 v129, 0
	s_movk_i32 s26, 0x2000
	v_or_b32_e32 v130, 0x5c00, v156
	s_movk_i32 s27, 0x6000
	v_or_b32_e32 v132, 0x6000, v156
	v_or_b32_e32 v134, 0x6400, v156
	v_or_b32_e32 v136, 0x6800, v156
	v_or_b32_e32 v138, 0x6c00, v156
	v_or_b32_e32 v140, 0x7000, v156
	v_or_b32_e32 v142, 0x7400, v156
	v_or_b32_e32 v144, 0x7800, v156
	v_cmp_gt_u32_e64 s[4:5], s4, v146
	v_cmp_gt_u32_e64 s[6:7], s6, v156
	s_movk_i32 s29, 0x3ff
	s_mov_b32 s30, 0xb300000
	v_lshlrev_b32_e32 v128, 4, v156
	v_lshlrev_b32_e32 v133, 4, v2
	s_mov_b32 s31, 0xa000
	v_lshlrev_b32_e32 v135, 4, v4
	s_mov_b32 s33, 0xe000
	v_lshlrev_b32_e32 v137, 4, v6
	s_mov_b32 s34, 0x12000
	v_lshlrev_b32_e32 v139, 4, v8
	s_mov_b32 s35, 0x16000
	v_lshlrev_b32_e32 v141, 4, v10
	s_mov_b32 s38, 0x1a000
	v_lshlrev_b32_e32 v143, 4, v12
	s_mov_b32 s39, 0x1e000
	v_lshlrev_b32_e32 v145, 4, v14
	s_mov_b32 s44, 0x22000
	v_lshlrev_b32_e32 v147, 4, v16
	s_mov_b32 s45, 0x26000
	v_lshlrev_b32_e32 v152, 4, v18
	s_mov_b32 s46, 0x2a000
	v_lshlrev_b32_e32 v153, 4, v20
	s_mov_b32 s47, 0x2e000
	v_lshlrev_b32_e32 v154, 4, v22
	s_mov_b32 s48, 0x32000
	v_lshlrev_b32_e32 v155, 4, v24
	s_mov_b32 s49, 0x36000
	v_lshlrev_b32_e32 v157, 4, v26
	s_mov_b32 s50, 0x3a000
	v_lshlrev_b32_e32 v158, 4, v28
	s_mov_b32 s51, 0x3e000
	s_mov_b32 s52, 0x42000
	s_mov_b32 s53, 0x46000
	s_mov_b32 s54, 0x4a000
	s_mov_b32 s55, 0x4e000
	s_mov_b32 s56, 0x52000
	s_mov_b32 s57, 0x56000
	s_mov_b32 s58, 0x5a000
	s_mov_b32 s59, 0x5e000
	s_mov_b32 s60, 0x62000
	s_mov_b32 s61, 0x66000
	s_mov_b32 s62, 0x6a000
	s_mov_b32 s63, 0x6e000
	s_mov_b32 s64, 0x72000
	v_cmp_ne_u32_e64 s[8:9], 1, v0
	v_mov_b32_e32 v159, s28
	v_lshlrev_b32_e32 v160, 4, v30
	v_lshlrev_b32_e32 v161, 4, v32
	v_lshlrev_b32_e32 v162, 4, v34
	v_lshlrev_b32_e32 v163, 4, v36
	v_lshlrev_b32_e32 v164, 4, v38
	v_lshlrev_b32_e32 v165, 4, v40
	v_lshlrev_b32_e32 v166, 4, v42
	s_branch .LBB0_1109
